# residual epilogues of out-proj and FFN-down GEMMs de-serialised: 4 batches of 8 rows, all loads of a batch first, counted vmcnt(14) per row
# speedup vs baseline: 1.0641x; 1.0204x over previous
.LBB0_39:
	ds_read_b128 v[188:191], v160
	ds_read_b128 v[192:195], v160 offset:32
	ds_read_b128 v[196:199], v161 offset:36864
	ds_read_b128 v[200:203], v161 offset:36896
	ds_read_b128 v[204:207], v160 offset:4608
	ds_read_b128 v[208:211], v160 offset:4640
	ds_read_b128 v[212:215], v161 offset:41472
	ds_read_b128 v[216:219], v161 offset:41504
	s_add_i32 s47, s50, 2
	s_waitcnt lgkmcnt(5)
	v_mfma_f32_32x32x16_bf16 v[50:65], v[188:191], v[196:199], v[50:65]
	s_waitcnt vmcnt(15)
	ds_write_b128 v184, v[66:69] offset:18432
	s_cmp_lt_u32 s47, 41
	s_cselect_b64 s[52:53], -1, 0
	s_and_b64 s[20:21], s[52:53], exec
	s_cselect_b32 s20, 0, 0x1ffffd4
	s_add_i32 s20, s20, s50
	s_lshl_b32 s51, s20, 7
	s_waitcnt lgkmcnt(2)
	v_mfma_f32_32x32x16_bf16 v[34:49], v[188:191], v[212:215], v[34:49]
	s_waitcnt vmcnt(14)
	ds_write_b128 v184, v[74:77] offset:55296
	s_add_i32 s56, s51, 0x280
	s_and_b64 s[20:21], s[52:53], exec
	s_cselect_b32 s21, s27, s41
	s_cselect_b32 s20, s40, s31
	s_and_b32 s21, s21, 0xffff
	s_and_b64 s[52:53], s[52:53], exec
	s_waitcnt lgkmcnt(5)
	v_mfma_f32_32x32x16_bf16 v[16:31], v[204:207], v[196:199], v[16:31]
	s_waitcnt vmcnt(13)
	ds_write_b128 v185, v[70:73] offset:18432
	s_cselect_b32 s53, s30, s46
	s_cselect_b32 s52, s44, s45
	s_and_b32 s53, s53, 0xffff
	s_mov_b32 s54, s22
	s_mov_b32 s55, s23
	s_waitcnt lgkmcnt(4)
	v_mfma_f32_32x32x16_bf16 v[0:15], v[204:207], v[212:215], v[0:15]
	s_waitcnt vmcnt(12)
	ds_write_b128 v185, v[82:85] offset:55296
	s_waitcnt lgkmcnt(8)
	v_mfma_f32_32x32x16_bf16 v[50:65], v[192:195], v[200:203], v[50:65]
	ds_read_b128 v[220:223], v160 offset:64
	ds_read_b128 v[142:145], v160 offset:96
	s_waitcnt vmcnt(11)
	ds_write_b128 v186, v[78:81] offset:18432
	s_waitcnt lgkmcnt(7)
	v_mfma_f32_32x32x16_bf16 v[34:49], v[192:195], v[216:219], v[34:49]
	ds_read_b128 v[154:157], v161 offset:36928
	ds_read_b128 v[138:141], v161 offset:36960
	s_waitcnt vmcnt(10)
	ds_write_b128 v186, v[90:93] offset:55296
	s_waitcnt lgkmcnt(12)
	v_mfma_f32_32x32x16_bf16 v[16:31], v[208:211], v[200:203], v[16:31]
	ds_read_b128 v[146:149], v160 offset:4672
	ds_read_b128 v[130:133], v160 offset:4704
	s_waitcnt vmcnt(9)
	ds_write_b128 v187, v[86:89] offset:18432
	s_waitcnt lgkmcnt(13)
	v_mfma_f32_32x32x16_bf16 v[0:15], v[208:211], v[216:219], v[0:15]
	ds_read_b128 v[150:153], v161 offset:41536
	ds_read_b128 v[134:137], v161 offset:41568
	s_waitcnt vmcnt(8)
	ds_write_b128 v187, v[94:97] offset:55296
	s_waitcnt lgkmcnt(8)
	v_mfma_f32_32x32x16_bf16 v[50:65], v[220:223], v[154:157], v[50:65]
	buffer_load_dwordx4 v[66:69], v180, s[20:23], s56 offen
	s_waitcnt lgkmcnt(2)
	v_mfma_f32_32x32x16_bf16 v[34:49], v[220:223], v[150:153], v[34:49]
	buffer_load_dwordx4 v[74:77], v180, s[52:55], s56 offen
	s_add_i32 s56, s51, 0x2c280
	s_waitcnt lgkmcnt(5)
	v_mfma_f32_32x32x16_bf16 v[16:31], v[146:149], v[154:157], v[16:31]
	buffer_load_dwordx4 v[70:73], v180, s[20:23], s56 offen
	s_waitcnt lgkmcnt(2)
	v_mfma_f32_32x32x16_bf16 v[0:15], v[146:149], v[150:153], v[0:15]
	buffer_load_dwordx4 v[82:85], v180, s[52:55], s56 offen
	s_add_i32 s56, s51, 0x58280
	s_add_i32 s51, s51, 0x84280
	s_waitcnt lgkmcnt(7)
	v_mfma_f32_32x32x16_bf16 v[50:65], v[142:145], v[138:141], v[50:65]
	buffer_load_dwordx4 v[78:81], v180, s[20:23], s56 offen
	s_waitcnt lgkmcnt(1)
	v_mfma_f32_32x32x16_bf16 v[34:49], v[142:145], v[134:137], v[34:49]
	buffer_load_dwordx4 v[90:93], v180, s[52:55], s56 offen
	s_waitcnt lgkmcnt(4)
	v_mfma_f32_32x32x16_bf16 v[16:31], v[130:133], v[138:141], v[16:31]
	buffer_load_dwordx4 v[86:89], v180, s[20:23], s51 offen
	s_waitcnt lgkmcnt(1)
	v_mfma_f32_32x32x16_bf16 v[0:15], v[130:133], v[134:137], v[0:15]
	buffer_load_dwordx4 v[94:97], v180, s[52:55], s51 offen
	s_waitcnt lgkmcnt(0)
	s_barrier
	ds_read_b128 v[188:191], v160 offset:18432
	ds_read_b128 v[192:195], v160 offset:18464
	ds_read_b128 v[196:199], v161 offset:55296
	ds_read_b128 v[200:203], v161 offset:55328
	ds_read_b128 v[204:207], v160 offset:23040
	ds_read_b128 v[208:211], v160 offset:23072
	ds_read_b128 v[212:215], v161 offset:59904
	ds_read_b128 v[216:219], v161 offset:59936
	s_waitcnt lgkmcnt(5)
	v_mfma_f32_32x32x16_bf16 v[50:65], v[188:191], v[196:199], v[50:65]
	s_waitcnt vmcnt(15)
	ds_write_b128 v184, v[98:101]
	s_cmp_lt_u32 s47, 40
	s_cselect_b64 s[52:53], -1, 0
	s_and_b64 s[20:21], s[52:53], exec
	s_cselect_b32 s20, 0, 0x1ffffd4
	s_add_i32 s20, s20, s50
	s_lshl_b32 s56, s20, 7
	s_waitcnt lgkmcnt(2)
	v_mfma_f32_32x32x16_bf16 v[34:49], v[188:191], v[212:215], v[34:49]
	s_waitcnt vmcnt(14)
	ds_write_b128 v184, v[106:109] offset:36864
	s_add_i32 s57, s56, 0x300
	s_and_b64 s[20:21], s[52:53], exec
	s_cselect_b32 s21, s27, s41
	s_cselect_b32 s20, s40, s31
	s_and_b32 s21, s21, 0xffff
	s_and_b64 s[50:51], s[52:53], exec
	s_waitcnt lgkmcnt(5)
	v_mfma_f32_32x32x16_bf16 v[16:31], v[204:207], v[196:199], v[16:31]
	s_waitcnt vmcnt(13)
	ds_write_b128 v185, v[102:105]
	s_cselect_b32 s50, s30, s46
	s_cselect_b32 s52, s44, s45
	s_and_b32 s53, s50, 0xffff
	s_add_i32 s50, s56, 0x2c300
	s_waitcnt lgkmcnt(4)
	v_mfma_f32_32x32x16_bf16 v[0:15], v[204:207], v[212:215], v[0:15]
	s_waitcnt vmcnt(12)
	ds_write_b128 v185, v[114:117] offset:36864
	s_waitcnt lgkmcnt(8)
	v_mfma_f32_32x32x16_bf16 v[50:65], v[192:195], v[200:203], v[50:65]
	ds_read_b128 v[220:223], v160 offset:18496
	ds_read_b128 v[142:145], v160 offset:18528
	s_waitcnt vmcnt(11)
	ds_write_b128 v186, v[110:113]
	s_waitcnt lgkmcnt(7)
	v_mfma_f32_32x32x16_bf16 v[34:49], v[192:195], v[216:219], v[34:49]
	ds_read_b128 v[154:157], v161 offset:55360
	ds_read_b128 v[138:141], v161 offset:55392
	s_waitcnt vmcnt(10)
	ds_write_b128 v186, v[122:125] offset:36864
	s_waitcnt lgkmcnt(12)
	v_mfma_f32_32x32x16_bf16 v[16:31], v[208:211], v[200:203], v[16:31]
	ds_read_b128 v[146:149], v160 offset:23104
	ds_read_b128 v[130:133], v160 offset:23136
	s_waitcnt vmcnt(9)
	ds_write_b128 v187, v[118:121]
	s_waitcnt lgkmcnt(13)
	v_mfma_f32_32x32x16_bf16 v[0:15], v[208:211], v[216:219], v[0:15]
	ds_read_b128 v[150:153], v161 offset:59968
	ds_read_b128 v[134:137], v161 offset:60000
	s_waitcnt vmcnt(8)
	ds_write_b128 v187, v[126:129] offset:36864
	s_waitcnt lgkmcnt(8)
	v_mfma_f32_32x32x16_bf16 v[50:65], v[220:223], v[154:157], v[50:65]
	buffer_load_dwordx4 v[98:101], v180, s[20:23], s57 offen
	s_waitcnt lgkmcnt(2)
	v_mfma_f32_32x32x16_bf16 v[34:49], v[220:223], v[150:153], v[34:49]
	buffer_load_dwordx4 v[106:109], v180, s[52:55], s57 offen
	s_waitcnt lgkmcnt(5)
	v_mfma_f32_32x32x16_bf16 v[16:31], v[146:149], v[154:157], v[16:31]
	buffer_load_dwordx4 v[102:105], v180, s[20:23], s50 offen
	s_waitcnt lgkmcnt(2)
	v_mfma_f32_32x32x16_bf16 v[0:15], v[146:149], v[150:153], v[0:15]
	buffer_load_dwordx4 v[114:117], v180, s[52:55], s50 offen
	s_add_i32 s50, s56, 0x58300
	s_add_i32 s56, s56, 0x84300
	s_waitcnt lgkmcnt(7)
	v_mfma_f32_32x32x16_bf16 v[50:65], v[142:145], v[138:141], v[50:65]
	buffer_load_dwordx4 v[110:113], v180, s[20:23], s50 offen
	s_waitcnt lgkmcnt(1)
	v_mfma_f32_32x32x16_bf16 v[34:49], v[142:145], v[134:137], v[34:49]
	buffer_load_dwordx4 v[122:125], v180, s[52:55], s50 offen
	s_waitcnt lgkmcnt(4)
	v_mfma_f32_32x32x16_bf16 v[16:31], v[130:133], v[138:141], v[16:31]
	buffer_load_dwordx4 v[118:121], v180, s[20:23], s56 offen
	s_waitcnt lgkmcnt(1)
	v_mfma_f32_32x32x16_bf16 v[0:15], v[130:133], v[134:137], v[0:15]
	buffer_load_dwordx4 v[126:129], v180, s[52:55], s56 offen
	s_cmp_gt_u32 s47, 41
	s_mov_b32 s50, s47
	s_waitcnt lgkmcnt(0)
	s_barrier
	s_cbranch_scc0 .LBB0_39
	s_cmpk_lt_i32 s25, 0x80
	s_cselect_b32 s20, s0, 0
	s_add_i32 s21, s20, 0xffffe000
	s_lshr_b32 s21, s21, 10
	s_add_i32 s21, s21, 1
	s_cmpk_gt_i32 s20, 0x1fff
	v_readlane_b32 s30, v232, 27
	s_cselect_b32 s20, s21, 0
	s_mul_i32 s21, s30, 9
	s_add_i32 s20, s20, s21
	v_and_b32_e32 v32, 64, v32
	s_mul_hi_i32 s21, s20, 0x6000
	s_mulk_i32 s20, 0x6000
	s_add_u32 s20, s94, s20
	v_or3_b32 v32, s24, v32, v181
	v_add_u32_e32 v130, s0, v183
	s_addc_u32 s21, s95, s21
	v_lshlrev_b32_e32 v131, 2, v182
	v_or_b32_e32 v132, s38, v32
	s_add_u32 s20, s20, 0x6025000
	v_lshlrev_b32_e32 v142, 2, v32
	v_or_b32_e32 v130, v130, v131
	v_ashrrev_i32_e32 v133, 31, v132
	s_addc_u32 s21, s21, 0
	s_lshl_b64 s[0:1], s[0:1], 12
	v_lshlrev_b32_e32 v136, 3, v130
	v_or_b32_e32 v130, 0x80, v142
	v_lshlrev_b64 v[132:133], 2, v[132:133]
	v_lshl_add_u64 v[138:139], v[32:33], 0, s[38:39]
	s_add_u32 s0, s92, s0
	v_or_b32_e32 v137, v131, v183
	global_load_dword v131, v142, s[20:21]
	v_lshl_add_u64 v[134:135], s[14:15], 0, v[132:133]
	global_load_dword v130, v130, s[20:21]
	v_lshlrev_b64 v[138:139], 2, v[138:139]
	v_readlane_b32 s20, v235, 38
	s_addc_u32 s1, s93, s1
	global_load_dword v134, v[134:135], off
	v_lshl_add_u64 v[140:141], s[14:15], 0, v[138:139]
	v_lshl_add_u64 v[132:133], s[16:17], 0, v[132:133]
	v_lshl_add_u64 v[138:139], s[16:17], 0, v[138:139]
	v_readlane_b32 s21, v235, 39
	v_lshl_or_b32 v135, v137, 12, v142
	global_load_dword v133, v[132:133], off
	v_readlane_b32 s52, v233, 61
	global_load_dword v132, v[138:139], off offset:128
	global_load_dword v32, v[140:141], off offset:128
	v_readlane_b32 s31, v232, 28
	v_readlane_b32 s62, v232, 7
	v_readlane_b32 s63, v232, 8
	s_and_b64 vcc, exec, s[42:43]
	s_mov_b32 s31, s37
	v_readlane_b32 s53, v233, 62
	v_readlane_b32 s56, v232, 1
	v_readlane_b32 s57, v232, 2
	v_readlane_b32 s58, v232, 3
	v_readlane_b32 s59, v232, 4
	v_readlane_b32 s60, v232, 5
	v_readlane_b32 s61, v232, 6
	v_readlane_b32 s64, v232, 9
	v_readlane_b32 s65, v232, 10
	v_readlane_b32 s66, v232, 11
	v_readlane_b32 s67, v232, 12
	v_readlane_b32 s63, v235, 21
	s_movk_i32 s51, 0x3fff
	v_readlane_b32 s62, v232, 31
	v_readlane_b32 s54, v233, 63
	v_readlane_b32 s55, v232, 0
	global_load_dwordx2 v[188:189], v136, s[20:21]
	global_load_dwordx2 v[190:191], v136, s[20:21] offset:8
	global_load_dwordx2 v[192:193], v136, s[20:21] offset:16
	global_load_dwordx2 v[194:195], v136, s[20:21] offset:24
	global_load_dwordx2 v[196:197], v136, s[20:21] offset:64
	global_load_dwordx2 v[198:199], v136, s[20:21] offset:72
	global_load_dwordx2 v[200:201], v136, s[20:21] offset:80
	global_load_dwordx2 v[202:203], v136, s[20:21] offset:88
	v_mov_b32_e32 v204, v135
	global_load_dword v212, v204, s[0:1]
	global_load_dword v213, v204, s[0:1] offset:128
	v_or_b32_e32 v205, 0x1000, v135
	global_load_dword v214, v205, s[0:1]
	global_load_dword v215, v205, s[0:1] offset:128
	v_or_b32_e32 v206, 0x2000, v135
	global_load_dword v216, v206, s[0:1]
	global_load_dword v217, v206, s[0:1] offset:128
	v_or_b32_e32 v207, 0x3000, v135
	global_load_dword v218, v207, s[0:1]
	global_load_dword v219, v207, s[0:1] offset:128
	v_or_b32_e32 v208, 0x8000, v135
	global_load_dword v220, v208, s[0:1]
	global_load_dword v221, v208, s[0:1] offset:128
	v_or_b32_e32 v209, 0x9000, v135
	global_load_dword v222, v209, s[0:1]
	global_load_dword v223, v209, s[0:1] offset:128
	v_or_b32_e32 v210, 0xa000, v135
	global_load_dword v224, v210, s[0:1]
	global_load_dword v225, v210, s[0:1] offset:128
	v_or_b32_e32 v211, 0xb000, v135
	global_load_dword v226, v211, s[0:1]
	global_load_dword v227, v211, s[0:1] offset:128
	s_waitcnt vmcnt(14)
	v_sub_f32_e32 v212, v212, v188
	v_sub_f32_e32 v213, v213, v188
	v_mul_f32_e32 v212, v189, v212
	v_mul_f32_e32 v213, v189, v213
	v_fma_f32 v212, v134, v212, v133
	v_fma_f32 v213, v32, v213, v132
	v_mul_f32_e32 v212, 0x3fd744fd, v212
	v_mul_f32_e32 v213, 0x3fd744fd, v213
	v_fmac_f32_e32 v212, v50, v131
	v_fmac_f32_e32 v213, v34, v130
	global_store_dword v204, v212, s[0:1]
	global_store_dword v204, v213, s[0:1] offset:128
	s_waitcnt vmcnt(14)
	v_sub_f32_e32 v214, v214, v190
	v_sub_f32_e32 v215, v215, v190
	v_mul_f32_e32 v214, v191, v214
	v_mul_f32_e32 v215, v191, v215
	v_fma_f32 v214, v134, v214, v133
	v_fma_f32 v215, v32, v215, v132
	v_mul_f32_e32 v214, 0x3fd744fd, v214
	v_mul_f32_e32 v215, 0x3fd744fd, v215
	v_fmac_f32_e32 v214, v51, v131
	v_fmac_f32_e32 v215, v35, v130
	global_store_dword v205, v214, s[0:1]
	global_store_dword v205, v215, s[0:1] offset:128
	s_waitcnt vmcnt(14)
	v_sub_f32_e32 v216, v216, v192
	v_sub_f32_e32 v217, v217, v192
	v_mul_f32_e32 v216, v193, v216
	v_mul_f32_e32 v217, v193, v217
	v_fma_f32 v216, v134, v216, v133
	v_fma_f32 v217, v32, v217, v132
	v_mul_f32_e32 v216, 0x3fd744fd, v216
	v_mul_f32_e32 v217, 0x3fd744fd, v217
	v_fmac_f32_e32 v216, v52, v131
	v_fmac_f32_e32 v217, v36, v130
	global_store_dword v206, v216, s[0:1]
	global_store_dword v206, v217, s[0:1] offset:128
	s_waitcnt vmcnt(14)
	v_sub_f32_e32 v218, v218, v194
	v_sub_f32_e32 v219, v219, v194
	v_mul_f32_e32 v218, v195, v218
	v_mul_f32_e32 v219, v195, v219
	v_fma_f32 v218, v134, v218, v133
	v_fma_f32 v219, v32, v219, v132
	v_mul_f32_e32 v218, 0x3fd744fd, v218
	v_mul_f32_e32 v219, 0x3fd744fd, v219
	v_fmac_f32_e32 v218, v53, v131
	v_fmac_f32_e32 v219, v37, v130
	global_store_dword v207, v218, s[0:1]
	global_store_dword v207, v219, s[0:1] offset:128
	s_waitcnt vmcnt(14)
	v_sub_f32_e32 v220, v220, v196
	v_sub_f32_e32 v221, v221, v196
	v_mul_f32_e32 v220, v197, v220
	v_mul_f32_e32 v221, v197, v221
	v_fma_f32 v220, v134, v220, v133
	v_fma_f32 v221, v32, v221, v132
	v_mul_f32_e32 v220, 0x3fd744fd, v220
	v_mul_f32_e32 v221, 0x3fd744fd, v221
	v_fmac_f32_e32 v220, v54, v131
	v_fmac_f32_e32 v221, v38, v130
	global_store_dword v208, v220, s[0:1]
	global_store_dword v208, v221, s[0:1] offset:128
	s_waitcnt vmcnt(14)
	v_sub_f32_e32 v222, v222, v198
	v_sub_f32_e32 v223, v223, v198
	v_mul_f32_e32 v222, v199, v222
	v_mul_f32_e32 v223, v199, v223
	v_fma_f32 v222, v134, v222, v133
	v_fma_f32 v223, v32, v223, v132
	v_mul_f32_e32 v222, 0x3fd744fd, v222
	v_mul_f32_e32 v223, 0x3fd744fd, v223
	v_fmac_f32_e32 v222, v55, v131
	v_fmac_f32_e32 v223, v39, v130
	global_store_dword v209, v222, s[0:1]
	global_store_dword v209, v223, s[0:1] offset:128
	s_waitcnt vmcnt(14)
	v_sub_f32_e32 v224, v224, v200
	v_sub_f32_e32 v225, v225, v200
	v_mul_f32_e32 v224, v201, v224
	v_mul_f32_e32 v225, v201, v225
	v_fma_f32 v224, v134, v224, v133
	v_fma_f32 v225, v32, v225, v132
	v_mul_f32_e32 v224, 0x3fd744fd, v224
	v_mul_f32_e32 v225, 0x3fd744fd, v225
	v_fmac_f32_e32 v224, v56, v131
	v_fmac_f32_e32 v225, v40, v130
	global_store_dword v210, v224, s[0:1]
	global_store_dword v210, v225, s[0:1] offset:128
	s_waitcnt vmcnt(14)
	v_sub_f32_e32 v226, v226, v202
	v_sub_f32_e32 v227, v227, v202
	v_mul_f32_e32 v226, v203, v226
	v_mul_f32_e32 v227, v203, v227
	v_fma_f32 v226, v134, v226, v133
	v_fma_f32 v227, v32, v227, v132
	v_mul_f32_e32 v226, 0x3fd744fd, v226
	v_mul_f32_e32 v227, 0x3fd744fd, v227
	v_fmac_f32_e32 v226, v57, v131
	v_fmac_f32_e32 v227, v41, v130
	global_store_dword v211, v226, s[0:1]
	global_store_dword v211, v227, s[0:1] offset:128
	global_load_dwordx2 v[188:189], v136, s[20:21] offset:128
	global_load_dwordx2 v[190:191], v136, s[20:21] offset:136
	global_load_dwordx2 v[192:193], v136, s[20:21] offset:144
	global_load_dwordx2 v[194:195], v136, s[20:21] offset:152
	global_load_dwordx2 v[196:197], v136, s[20:21] offset:192
	global_load_dwordx2 v[198:199], v136, s[20:21] offset:200
	global_load_dwordx2 v[200:201], v136, s[20:21] offset:208
	global_load_dwordx2 v[202:203], v136, s[20:21] offset:216
	v_or_b32_e32 v204, 0x10000, v135
	global_load_dword v212, v204, s[0:1]
	global_load_dword v213, v204, s[0:1] offset:128
	v_or_b32_e32 v205, 0x11000, v135
	global_load_dword v214, v205, s[0:1]
	global_load_dword v215, v205, s[0:1] offset:128
	v_or_b32_e32 v206, 0x12000, v135
	global_load_dword v216, v206, s[0:1]
	global_load_dword v217, v206, s[0:1] offset:128
	v_or_b32_e32 v207, 0x13000, v135
	global_load_dword v218, v207, s[0:1]
	global_load_dword v219, v207, s[0:1] offset:128
	v_or_b32_e32 v208, 0x18000, v135
	global_load_dword v220, v208, s[0:1]
	global_load_dword v221, v208, s[0:1] offset:128
	v_or_b32_e32 v209, 0x19000, v135
	global_load_dword v222, v209, s[0:1]
	global_load_dword v223, v209, s[0:1] offset:128
	v_or_b32_e32 v210, 0x1a000, v135
	global_load_dword v224, v210, s[0:1]
	global_load_dword v225, v210, s[0:1] offset:128
	v_or_b32_e32 v211, 0x1b000, v135
	global_load_dword v226, v211, s[0:1]
	global_load_dword v227, v211, s[0:1] offset:128
	s_waitcnt vmcnt(14)
	v_sub_f32_e32 v212, v212, v188
	v_sub_f32_e32 v213, v213, v188
	v_mul_f32_e32 v212, v189, v212
	v_mul_f32_e32 v213, v189, v213
	v_fma_f32 v212, v134, v212, v133
	v_fma_f32 v213, v32, v213, v132
	v_mul_f32_e32 v212, 0x3fd744fd, v212
	v_mul_f32_e32 v213, 0x3fd744fd, v213
	v_fmac_f32_e32 v212, v58, v131
	v_fmac_f32_e32 v213, v42, v130
	global_store_dword v204, v212, s[0:1]
	global_store_dword v204, v213, s[0:1] offset:128
	s_waitcnt vmcnt(14)
	v_sub_f32_e32 v214, v214, v190
	v_sub_f32_e32 v215, v215, v190
	v_mul_f32_e32 v214, v191, v214
	v_mul_f32_e32 v215, v191, v215
	v_fma_f32 v214, v134, v214, v133
	v_fma_f32 v215, v32, v215, v132
	v_mul_f32_e32 v214, 0x3fd744fd, v214
	v_mul_f32_e32 v215, 0x3fd744fd, v215
	v_fmac_f32_e32 v214, v59, v131
	v_fmac_f32_e32 v215, v43, v130
	global_store_dword v205, v214, s[0:1]
	global_store_dword v205, v215, s[0:1] offset:128
	s_waitcnt vmcnt(14)
	v_sub_f32_e32 v216, v216, v192
	v_sub_f32_e32 v217, v217, v192
	v_mul_f32_e32 v216, v193, v216
	v_mul_f32_e32 v217, v193, v217
	v_fma_f32 v216, v134, v216, v133
	v_fma_f32 v217, v32, v217, v132
	v_mul_f32_e32 v216, 0x3fd744fd, v216
	v_mul_f32_e32 v217, 0x3fd744fd, v217
	v_fmac_f32_e32 v216, v60, v131
	v_fmac_f32_e32 v217, v44, v130
	global_store_dword v206, v216, s[0:1]
	global_store_dword v206, v217, s[0:1] offset:128
	s_waitcnt vmcnt(14)
	v_sub_f32_e32 v218, v218, v194
	v_sub_f32_e32 v219, v219, v194
	v_mul_f32_e32 v218, v195, v218
	v_mul_f32_e32 v219, v195, v219
	v_fma_f32 v218, v134, v218, v133
	v_fma_f32 v219, v32, v219, v132
	v_mul_f32_e32 v218, 0x3fd744fd, v218
	v_mul_f32_e32 v219, 0x3fd744fd, v219
	v_fmac_f32_e32 v218, v61, v131
	v_fmac_f32_e32 v219, v45, v130
	global_store_dword v207, v218, s[0:1]
	global_store_dword v207, v219, s[0:1] offset:128
	s_waitcnt vmcnt(14)
	v_sub_f32_e32 v220, v220, v196
	v_sub_f32_e32 v221, v221, v196
	v_mul_f32_e32 v220, v197, v220
	v_mul_f32_e32 v221, v197, v221
	v_fma_f32 v220, v134, v220, v133
	v_fma_f32 v221, v32, v221, v132
	v_mul_f32_e32 v220, 0x3fd744fd, v220
	v_mul_f32_e32 v221, 0x3fd744fd, v221
	v_fmac_f32_e32 v220, v62, v131
	v_fmac_f32_e32 v221, v46, v130
	global_store_dword v208, v220, s[0:1]
	global_store_dword v208, v221, s[0:1] offset:128
	s_waitcnt vmcnt(14)
	v_sub_f32_e32 v222, v222, v198
	v_sub_f32_e32 v223, v223, v198
	v_mul_f32_e32 v222, v199, v222
	v_mul_f32_e32 v223, v199, v223
	v_fma_f32 v222, v134, v222, v133
	v_fma_f32 v223, v32, v223, v132
	v_mul_f32_e32 v222, 0x3fd744fd, v222
	v_mul_f32_e32 v223, 0x3fd744fd, v223
	v_fmac_f32_e32 v222, v63, v131
	v_fmac_f32_e32 v223, v47, v130
	global_store_dword v209, v222, s[0:1]
	global_store_dword v209, v223, s[0:1] offset:128
	s_waitcnt vmcnt(14)
	v_sub_f32_e32 v224, v224, v200
	v_sub_f32_e32 v225, v225, v200
	v_mul_f32_e32 v224, v201, v224
	v_mul_f32_e32 v225, v201, v225
	v_fma_f32 v224, v134, v224, v133
	v_fma_f32 v225, v32, v225, v132
	v_mul_f32_e32 v224, 0x3fd744fd, v224
	v_mul_f32_e32 v225, 0x3fd744fd, v225
	v_fmac_f32_e32 v224, v64, v131
	v_fmac_f32_e32 v225, v48, v130
	global_store_dword v210, v224, s[0:1]
	global_store_dword v210, v225, s[0:1] offset:128
	s_waitcnt vmcnt(14)
	v_sub_f32_e32 v226, v226, v202
	v_sub_f32_e32 v227, v227, v202
	v_mul_f32_e32 v226, v203, v226
	v_mul_f32_e32 v227, v203, v227
	v_fma_f32 v226, v134, v226, v133
	v_fma_f32 v227, v32, v227, v132
	v_mul_f32_e32 v226, 0x3fd744fd, v226
	v_mul_f32_e32 v227, 0x3fd744fd, v227
	v_fmac_f32_e32 v226, v65, v131
	v_fmac_f32_e32 v227, v49, v130
	global_store_dword v211, v226, s[0:1]
	global_store_dword v211, v227, s[0:1] offset:128
	global_load_dwordx2 v[188:189], v136, s[20:21] offset:256
	global_load_dwordx2 v[190:191], v136, s[20:21] offset:264
	global_load_dwordx2 v[192:193], v136, s[20:21] offset:272
	global_load_dwordx2 v[194:195], v136, s[20:21] offset:280
	global_load_dwordx2 v[196:197], v136, s[20:21] offset:320
	global_load_dwordx2 v[198:199], v136, s[20:21] offset:328
	global_load_dwordx2 v[200:201], v136, s[20:21] offset:336
	global_load_dwordx2 v[202:203], v136, s[20:21] offset:344
	v_or_b32_e32 v204, 0x20000, v135
	global_load_dword v212, v204, s[0:1]
	global_load_dword v213, v204, s[0:1] offset:128
	v_or_b32_e32 v205, 0x21000, v135
	global_load_dword v214, v205, s[0:1]
	global_load_dword v215, v205, s[0:1] offset:128
	v_or_b32_e32 v206, 0x22000, v135
	global_load_dword v216, v206, s[0:1]
	global_load_dword v217, v206, s[0:1] offset:128
	v_or_b32_e32 v207, 0x23000, v135
	global_load_dword v218, v207, s[0:1]
	global_load_dword v219, v207, s[0:1] offset:128
	v_or_b32_e32 v208, 0x28000, v135
	global_load_dword v220, v208, s[0:1]
	global_load_dword v221, v208, s[0:1] offset:128
	v_or_b32_e32 v209, 0x29000, v135
	global_load_dword v222, v209, s[0:1]
	global_load_dword v223, v209, s[0:1] offset:128
	v_or_b32_e32 v210, 0x2a000, v135
	global_load_dword v224, v210, s[0:1]
	global_load_dword v225, v210, s[0:1] offset:128
	v_or_b32_e32 v211, 0x2b000, v135
	global_load_dword v226, v211, s[0:1]
	global_load_dword v227, v211, s[0:1] offset:128
	s_waitcnt vmcnt(14)
	v_sub_f32_e32 v212, v212, v188
	v_sub_f32_e32 v213, v213, v188
	v_mul_f32_e32 v212, v189, v212
	v_mul_f32_e32 v213, v189, v213
	v_fma_f32 v212, v134, v212, v133
	v_fma_f32 v213, v32, v213, v132
	v_mul_f32_e32 v212, 0x3fd744fd, v212
	v_mul_f32_e32 v213, 0x3fd744fd, v213
	v_fmac_f32_e32 v212, v16, v131
	v_fmac_f32_e32 v213, v0, v130
	global_store_dword v204, v212, s[0:1]
	global_store_dword v204, v213, s[0:1] offset:128
	s_waitcnt vmcnt(14)
	v_sub_f32_e32 v214, v214, v190
	v_sub_f32_e32 v215, v215, v190
	v_mul_f32_e32 v214, v191, v214
	v_mul_f32_e32 v215, v191, v215
	v_fma_f32 v214, v134, v214, v133
	v_fma_f32 v215, v32, v215, v132
	v_mul_f32_e32 v214, 0x3fd744fd, v214
	v_mul_f32_e32 v215, 0x3fd744fd, v215
	v_fmac_f32_e32 v214, v17, v131
	v_fmac_f32_e32 v215, v1, v130
	global_store_dword v205, v214, s[0:1]
	global_store_dword v205, v215, s[0:1] offset:128
	s_waitcnt vmcnt(14)
	v_sub_f32_e32 v216, v216, v192
	v_sub_f32_e32 v217, v217, v192
	v_mul_f32_e32 v216, v193, v216
	v_mul_f32_e32 v217, v193, v217
	v_fma_f32 v216, v134, v216, v133
	v_fma_f32 v217, v32, v217, v132
	v_mul_f32_e32 v216, 0x3fd744fd, v216
	v_mul_f32_e32 v217, 0x3fd744fd, v217
	v_fmac_f32_e32 v216, v18, v131
	v_fmac_f32_e32 v217, v2, v130
	global_store_dword v206, v216, s[0:1]
	global_store_dword v206, v217, s[0:1] offset:128
	s_waitcnt vmcnt(14)
	v_sub_f32_e32 v218, v218, v194
	v_sub_f32_e32 v219, v219, v194
	v_mul_f32_e32 v218, v195, v218
	v_mul_f32_e32 v219, v195, v219
	v_fma_f32 v218, v134, v218, v133
	v_fma_f32 v219, v32, v219, v132
	v_mul_f32_e32 v218, 0x3fd744fd, v218
	v_mul_f32_e32 v219, 0x3fd744fd, v219
	v_fmac_f32_e32 v218, v19, v131
	v_fmac_f32_e32 v219, v3, v130
	global_store_dword v207, v218, s[0:1]
	global_store_dword v207, v219, s[0:1] offset:128
	s_waitcnt vmcnt(14)
	v_sub_f32_e32 v220, v220, v196
	v_sub_f32_e32 v221, v221, v196
	v_mul_f32_e32 v220, v197, v220
	v_mul_f32_e32 v221, v197, v221
	v_fma_f32 v220, v134, v220, v133
	v_fma_f32 v221, v32, v221, v132
	v_mul_f32_e32 v220, 0x3fd744fd, v220
	v_mul_f32_e32 v221, 0x3fd744fd, v221
	v_fmac_f32_e32 v220, v20, v131
	v_fmac_f32_e32 v221, v4, v130
	global_store_dword v208, v220, s[0:1]
	global_store_dword v208, v221, s[0:1] offset:128
	s_waitcnt vmcnt(14)
	v_sub_f32_e32 v222, v222, v198
	v_sub_f32_e32 v223, v223, v198
	v_mul_f32_e32 v222, v199, v222
	v_mul_f32_e32 v223, v199, v223
	v_fma_f32 v222, v134, v222, v133
	v_fma_f32 v223, v32, v223, v132
	v_mul_f32_e32 v222, 0x3fd744fd, v222
	v_mul_f32_e32 v223, 0x3fd744fd, v223
	v_fmac_f32_e32 v222, v21, v131
	v_fmac_f32_e32 v223, v5, v130
	global_store_dword v209, v222, s[0:1]
	global_store_dword v209, v223, s[0:1] offset:128
	s_waitcnt vmcnt(14)
	v_sub_f32_e32 v224, v224, v200
	v_sub_f32_e32 v225, v225, v200
	v_mul_f32_e32 v224, v201, v224
	v_mul_f32_e32 v225, v201, v225
	v_fma_f32 v224, v134, v224, v133
	v_fma_f32 v225, v32, v225, v132
	v_mul_f32_e32 v224, 0x3fd744fd, v224
	v_mul_f32_e32 v225, 0x3fd744fd, v225
	v_fmac_f32_e32 v224, v22, v131
	v_fmac_f32_e32 v225, v6, v130
	global_store_dword v210, v224, s[0:1]
	global_store_dword v210, v225, s[0:1] offset:128
	s_waitcnt vmcnt(14)
	v_sub_f32_e32 v226, v226, v202
	v_sub_f32_e32 v227, v227, v202
	v_mul_f32_e32 v226, v203, v226
	v_mul_f32_e32 v227, v203, v227
	v_fma_f32 v226, v134, v226, v133
	v_fma_f32 v227, v32, v227, v132
	v_mul_f32_e32 v226, 0x3fd744fd, v226
	v_mul_f32_e32 v227, 0x3fd744fd, v227
	v_fmac_f32_e32 v226, v23, v131
	v_fmac_f32_e32 v227, v7, v130
	global_store_dword v211, v226, s[0:1]
	global_store_dword v211, v227, s[0:1] offset:128
	global_load_dwordx2 v[188:189], v136, s[20:21] offset:384
	global_load_dwordx2 v[190:191], v136, s[20:21] offset:392
	global_load_dwordx2 v[192:193], v136, s[20:21] offset:400
	global_load_dwordx2 v[194:195], v136, s[20:21] offset:408
	global_load_dwordx2 v[196:197], v136, s[20:21] offset:448
	global_load_dwordx2 v[198:199], v136, s[20:21] offset:456
	global_load_dwordx2 v[200:201], v136, s[20:21] offset:464
	global_load_dwordx2 v[202:203], v136, s[20:21] offset:472
	v_or_b32_e32 v204, 0x30000, v135
	global_load_dword v212, v204, s[0:1]
	global_load_dword v213, v204, s[0:1] offset:128
	v_or_b32_e32 v205, 0x31000, v135
	global_load_dword v214, v205, s[0:1]
	global_load_dword v215, v205, s[0:1] offset:128
	v_or_b32_e32 v206, 0x32000, v135
	global_load_dword v216, v206, s[0:1]
	global_load_dword v217, v206, s[0:1] offset:128
	v_or_b32_e32 v207, 0x33000, v135
	global_load_dword v218, v207, s[0:1]
	global_load_dword v219, v207, s[0:1] offset:128
	v_or_b32_e32 v208, 0x38000, v135
	global_load_dword v220, v208, s[0:1]
	global_load_dword v221, v208, s[0:1] offset:128
	v_or_b32_e32 v209, 0x39000, v135
	global_load_dword v222, v209, s[0:1]
	global_load_dword v223, v209, s[0:1] offset:128
	v_or_b32_e32 v210, 0x3a000, v135
	global_load_dword v224, v210, s[0:1]
	global_load_dword v225, v210, s[0:1] offset:128
	v_or_b32_e32 v211, 0x3b000, v135
	global_load_dword v226, v211, s[0:1]
	global_load_dword v227, v211, s[0:1] offset:128
	s_waitcnt vmcnt(14)
	v_sub_f32_e32 v212, v212, v188
	v_sub_f32_e32 v213, v213, v188
	v_mul_f32_e32 v212, v189, v212
	v_mul_f32_e32 v213, v189, v213
	v_fma_f32 v212, v134, v212, v133
	v_fma_f32 v213, v32, v213, v132
	v_mul_f32_e32 v212, 0x3fd744fd, v212
	v_mul_f32_e32 v213, 0x3fd744fd, v213
	v_fmac_f32_e32 v212, v24, v131
	v_fmac_f32_e32 v213, v8, v130
	global_store_dword v204, v212, s[0:1]
	global_store_dword v204, v213, s[0:1] offset:128
	s_waitcnt vmcnt(14)
	v_sub_f32_e32 v214, v214, v190
	v_sub_f32_e32 v215, v215, v190
	v_mul_f32_e32 v214, v191, v214
	v_mul_f32_e32 v215, v191, v215
	v_fma_f32 v214, v134, v214, v133
	v_fma_f32 v215, v32, v215, v132
	v_mul_f32_e32 v214, 0x3fd744fd, v214
	v_mul_f32_e32 v215, 0x3fd744fd, v215
	v_fmac_f32_e32 v214, v25, v131
	v_fmac_f32_e32 v215, v9, v130
	global_store_dword v205, v214, s[0:1]
	global_store_dword v205, v215, s[0:1] offset:128
	s_waitcnt vmcnt(14)
	v_sub_f32_e32 v216, v216, v192
	v_sub_f32_e32 v217, v217, v192
	v_mul_f32_e32 v216, v193, v216
	v_mul_f32_e32 v217, v193, v217
	v_fma_f32 v216, v134, v216, v133
	v_fma_f32 v217, v32, v217, v132
	v_mul_f32_e32 v216, 0x3fd744fd, v216
	v_mul_f32_e32 v217, 0x3fd744fd, v217
	v_fmac_f32_e32 v216, v26, v131
	v_fmac_f32_e32 v217, v10, v130
	global_store_dword v206, v216, s[0:1]
	global_store_dword v206, v217, s[0:1] offset:128
	s_waitcnt vmcnt(14)
	v_sub_f32_e32 v218, v218, v194
	v_sub_f32_e32 v219, v219, v194
	v_mul_f32_e32 v218, v195, v218
	v_mul_f32_e32 v219, v195, v219
	v_fma_f32 v218, v134, v218, v133
	v_fma_f32 v219, v32, v219, v132
	v_mul_f32_e32 v218, 0x3fd744fd, v218
	v_mul_f32_e32 v219, 0x3fd744fd, v219
	v_fmac_f32_e32 v218, v27, v131
	v_fmac_f32_e32 v219, v11, v130
	global_store_dword v207, v218, s[0:1]
	global_store_dword v207, v219, s[0:1] offset:128
	s_waitcnt vmcnt(14)
	v_sub_f32_e32 v220, v220, v196
	v_sub_f32_e32 v221, v221, v196
	v_mul_f32_e32 v220, v197, v220
	v_mul_f32_e32 v221, v197, v221
	v_fma_f32 v220, v134, v220, v133
	v_fma_f32 v221, v32, v221, v132
	v_mul_f32_e32 v220, 0x3fd744fd, v220
	v_mul_f32_e32 v221, 0x3fd744fd, v221
	v_fmac_f32_e32 v220, v28, v131
	v_fmac_f32_e32 v221, v12, v130
	global_store_dword v208, v220, s[0:1]
	global_store_dword v208, v221, s[0:1] offset:128
	s_waitcnt vmcnt(14)
	v_sub_f32_e32 v222, v222, v198
	v_sub_f32_e32 v223, v223, v198
	v_mul_f32_e32 v222, v199, v222
	v_mul_f32_e32 v223, v199, v223
	v_fma_f32 v222, v134, v222, v133
	v_fma_f32 v223, v32, v223, v132
	v_mul_f32_e32 v222, 0x3fd744fd, v222
	v_mul_f32_e32 v223, 0x3fd744fd, v223
	v_fmac_f32_e32 v222, v29, v131
	v_fmac_f32_e32 v223, v13, v130
	global_store_dword v209, v222, s[0:1]
	global_store_dword v209, v223, s[0:1] offset:128
	s_waitcnt vmcnt(14)
	v_sub_f32_e32 v224, v224, v200
	v_sub_f32_e32 v225, v225, v200
	v_mul_f32_e32 v224, v201, v224
	v_mul_f32_e32 v225, v201, v225
	v_fma_f32 v224, v134, v224, v133
	v_fma_f32 v225, v32, v225, v132
	v_mul_f32_e32 v224, 0x3fd744fd, v224
	v_mul_f32_e32 v225, 0x3fd744fd, v225
	v_fmac_f32_e32 v224, v30, v131
	v_fmac_f32_e32 v225, v14, v130
	global_store_dword v210, v224, s[0:1]
	global_store_dword v210, v225, s[0:1] offset:128
	s_waitcnt vmcnt(14)
	v_sub_f32_e32 v226, v226, v202
	v_sub_f32_e32 v227, v227, v202
	v_mul_f32_e32 v226, v203, v226
	v_mul_f32_e32 v227, v203, v227
	v_fma_f32 v226, v134, v226, v133
	v_fma_f32 v227, v32, v227, v132
	v_mul_f32_e32 v226, 0x3fd744fd, v226
	v_mul_f32_e32 v227, 0x3fd744fd, v227
	v_fmac_f32_e32 v226, v31, v131
	v_fmac_f32_e32 v227, v15, v130
	global_store_dword v211, v226, s[0:1]
	global_store_dword v211, v227, s[0:1] offset:128
	s_mov_b64 s[20:21], 0
	s_cbranch_vccz .LBB0_34

.Lres_tail_77:
	s_and_b64 vcc, exec, s[42:43]
	s_mov_b64 s[0:1], 0
	s_mov_b32 s20, s41
	s_cbranch_vccnz .LBB0_148

.LBB0_83:
	v_add_u32_e32 v32, s28, v182
	v_lshlrev_b32_e32 v135, 2, v181
	v_or_b32_e32 v32, v32, v135
	v_readlane_b32 s24, v235, 38
	v_lshlrev_b32_e32 v32, 3, v32
	v_readlane_b32 s25, v235, 39
	s_and_b64 vcc, exec, s[38:39]
	v_readlane_b32 s63, v235, 21
	v_lshl_add_u64 v[130:131], s[24:25], 0, v[32:33]
	v_readlane_b32 s62, v232, 31
	v_or_b32_e32 v32, v135, v182
	v_lshl_or_b32 v32, v32, 12, v134
	s_add_u32 s20, s92, s20
	s_addc_u32 s21, s93, s21
	v_mov_b32_e32 v188, 0
	v_mov_b32_e32 v189, 1.0
	v_mov_b32_e32 v190, 0
	v_mov_b32_e32 v191, 1.0
	v_mov_b32_e32 v192, 0
	v_mov_b32_e32 v193, 1.0
	v_mov_b32_e32 v194, 0
	v_mov_b32_e32 v195, 1.0
	v_mov_b32_e32 v196, 0
	v_mov_b32_e32 v197, 1.0
	v_mov_b32_e32 v198, 0
	v_mov_b32_e32 v199, 1.0
	v_mov_b32_e32 v200, 0
	v_mov_b32_e32 v201, 1.0
	v_mov_b32_e32 v202, 0
	v_mov_b32_e32 v203, 1.0
	s_and_b64 vcc, exec, s[38:39]
	s_cbranch_vccnz .Lres77_ns0
	global_load_dwordx2 v[188:189], v[130:131], off
	global_load_dwordx2 v[190:191], v[130:131], off offset:8
	global_load_dwordx2 v[192:193], v[130:131], off offset:16
	global_load_dwordx2 v[194:195], v[130:131], off offset:24
	global_load_dwordx2 v[196:197], v[130:131], off offset:64
	global_load_dwordx2 v[198:199], v[130:131], off offset:72
	global_load_dwordx2 v[200:201], v[130:131], off offset:80
	global_load_dwordx2 v[202:203], v[130:131], off offset:88
.Lres77_ns0:
	v_mov_b32_e32 v204, v32
	global_load_dword v212, v204, s[0:1]
	global_load_dword v213, v204, s[0:1] offset:128
	v_or_b32_e32 v205, 0x1000, v32
	global_load_dword v214, v205, s[0:1]
	global_load_dword v215, v205, s[0:1] offset:128
	v_or_b32_e32 v206, 0x2000, v32
	global_load_dword v216, v206, s[0:1]
	global_load_dword v217, v206, s[0:1] offset:128
	v_or_b32_e32 v207, 0x3000, v32
	global_load_dword v218, v207, s[0:1]
	global_load_dword v219, v207, s[0:1] offset:128
	v_or_b32_e32 v208, 0x8000, v32
	global_load_dword v220, v208, s[0:1]
	global_load_dword v221, v208, s[0:1] offset:128
	v_or_b32_e32 v209, 0x9000, v32
	global_load_dword v222, v209, s[0:1]
	global_load_dword v223, v209, s[0:1] offset:128
	v_or_b32_e32 v210, 0xa000, v32
	global_load_dword v224, v210, s[0:1]
	global_load_dword v225, v210, s[0:1] offset:128
	v_or_b32_e32 v211, 0xb000, v32
	global_load_dword v226, v211, s[0:1]
	global_load_dword v227, v211, s[0:1] offset:128
	s_waitcnt vmcnt(14)
	v_sub_f32_e32 v212, v212, v188
	v_sub_f32_e32 v213, v213, v188
	v_mul_f32_e32 v212, v189, v212
	v_mul_f32_e32 v213, v189, v213
	v_fma_f32 v212, v141, v212, v138
	v_fma_f32 v213, v139, v213, v140
	v_mul_f32_e32 v212, 0x3fd744fd, v212
	v_mul_f32_e32 v213, 0x3fd744fd, v213
	v_fmac_f32_e32 v212, v50, v137
	v_fmac_f32_e32 v213, v34, v136
	global_store_dword v204, v212, s[20:21]
	global_store_dword v204, v213, s[20:21] offset:128
	s_waitcnt vmcnt(14)
	v_sub_f32_e32 v214, v214, v190
	v_sub_f32_e32 v215, v215, v190
	v_mul_f32_e32 v214, v191, v214
	v_mul_f32_e32 v215, v191, v215
	v_fma_f32 v214, v141, v214, v138
	v_fma_f32 v215, v139, v215, v140
	v_mul_f32_e32 v214, 0x3fd744fd, v214
	v_mul_f32_e32 v215, 0x3fd744fd, v215
	v_fmac_f32_e32 v214, v51, v137
	v_fmac_f32_e32 v215, v35, v136
	global_store_dword v205, v214, s[20:21]
	global_store_dword v205, v215, s[20:21] offset:128
	s_waitcnt vmcnt(14)
	v_sub_f32_e32 v216, v216, v192
	v_sub_f32_e32 v217, v217, v192
	v_mul_f32_e32 v216, v193, v216
	v_mul_f32_e32 v217, v193, v217
	v_fma_f32 v216, v141, v216, v138
	v_fma_f32 v217, v139, v217, v140
	v_mul_f32_e32 v216, 0x3fd744fd, v216
	v_mul_f32_e32 v217, 0x3fd744fd, v217
	v_fmac_f32_e32 v216, v52, v137
	v_fmac_f32_e32 v217, v36, v136
	global_store_dword v206, v216, s[20:21]
	global_store_dword v206, v217, s[20:21] offset:128
	s_waitcnt vmcnt(14)
	v_sub_f32_e32 v218, v218, v194
	v_sub_f32_e32 v219, v219, v194
	v_mul_f32_e32 v218, v195, v218
	v_mul_f32_e32 v219, v195, v219
	v_fma_f32 v218, v141, v218, v138
	v_fma_f32 v219, v139, v219, v140
	v_mul_f32_e32 v218, 0x3fd744fd, v218
	v_mul_f32_e32 v219, 0x3fd744fd, v219
	v_fmac_f32_e32 v218, v53, v137
	v_fmac_f32_e32 v219, v37, v136
	global_store_dword v207, v218, s[20:21]
	global_store_dword v207, v219, s[20:21] offset:128
	s_waitcnt vmcnt(14)
	v_sub_f32_e32 v220, v220, v196
	v_sub_f32_e32 v221, v221, v196
	v_mul_f32_e32 v220, v197, v220
	v_mul_f32_e32 v221, v197, v221
	v_fma_f32 v220, v141, v220, v138
	v_fma_f32 v221, v139, v221, v140
	v_mul_f32_e32 v220, 0x3fd744fd, v220
	v_mul_f32_e32 v221, 0x3fd744fd, v221
	v_fmac_f32_e32 v220, v54, v137
	v_fmac_f32_e32 v221, v38, v136
	global_store_dword v208, v220, s[20:21]
	global_store_dword v208, v221, s[20:21] offset:128
	s_waitcnt vmcnt(14)
	v_sub_f32_e32 v222, v222, v198
	v_sub_f32_e32 v223, v223, v198
	v_mul_f32_e32 v222, v199, v222
	v_mul_f32_e32 v223, v199, v223
	v_fma_f32 v222, v141, v222, v138
	v_fma_f32 v223, v139, v223, v140
	v_mul_f32_e32 v222, 0x3fd744fd, v222
	v_mul_f32_e32 v223, 0x3fd744fd, v223
	v_fmac_f32_e32 v222, v55, v137
	v_fmac_f32_e32 v223, v39, v136
	global_store_dword v209, v222, s[20:21]
	global_store_dword v209, v223, s[20:21] offset:128
	s_waitcnt vmcnt(14)
	v_sub_f32_e32 v224, v224, v200
	v_sub_f32_e32 v225, v225, v200
	v_mul_f32_e32 v224, v201, v224
	v_mul_f32_e32 v225, v201, v225
	v_fma_f32 v224, v141, v224, v138
	v_fma_f32 v225, v139, v225, v140
	v_mul_f32_e32 v224, 0x3fd744fd, v224
	v_mul_f32_e32 v225, 0x3fd744fd, v225
	v_fmac_f32_e32 v224, v56, v137
	v_fmac_f32_e32 v225, v40, v136
	global_store_dword v210, v224, s[20:21]
	global_store_dword v210, v225, s[20:21] offset:128
	s_waitcnt vmcnt(14)
	v_sub_f32_e32 v226, v226, v202
	v_sub_f32_e32 v227, v227, v202
	v_mul_f32_e32 v226, v203, v226
	v_mul_f32_e32 v227, v203, v227
	v_fma_f32 v226, v141, v226, v138
	v_fma_f32 v227, v139, v227, v140
	v_mul_f32_e32 v226, 0x3fd744fd, v226
	v_mul_f32_e32 v227, 0x3fd744fd, v227
	v_fmac_f32_e32 v226, v57, v137
	v_fmac_f32_e32 v227, v41, v136
	global_store_dword v211, v226, s[20:21]
	global_store_dword v211, v227, s[20:21] offset:128
	v_mov_b32_e32 v188, 0
	v_mov_b32_e32 v189, 1.0
	v_mov_b32_e32 v190, 0
	v_mov_b32_e32 v191, 1.0
	v_mov_b32_e32 v192, 0
	v_mov_b32_e32 v193, 1.0
	v_mov_b32_e32 v194, 0
	v_mov_b32_e32 v195, 1.0
	v_mov_b32_e32 v196, 0
	v_mov_b32_e32 v197, 1.0
	v_mov_b32_e32 v198, 0
	v_mov_b32_e32 v199, 1.0
	v_mov_b32_e32 v200, 0
	v_mov_b32_e32 v201, 1.0
	v_mov_b32_e32 v202, 0
	v_mov_b32_e32 v203, 1.0
	s_and_b64 vcc, exec, s[38:39]
	s_cbranch_vccnz .Lres77_ns1
	global_load_dwordx2 v[188:189], v[130:131], off offset:128
	global_load_dwordx2 v[190:191], v[130:131], off offset:136
	global_load_dwordx2 v[192:193], v[130:131], off offset:144
	global_load_dwordx2 v[194:195], v[130:131], off offset:152
	global_load_dwordx2 v[196:197], v[130:131], off offset:192
	global_load_dwordx2 v[198:199], v[130:131], off offset:200
	global_load_dwordx2 v[200:201], v[130:131], off offset:208
	global_load_dwordx2 v[202:203], v[130:131], off offset:216
.Lres77_ns1:
	v_or_b32_e32 v204, 0x10000, v32
	global_load_dword v212, v204, s[0:1]
	global_load_dword v213, v204, s[0:1] offset:128
	v_or_b32_e32 v205, 0x11000, v32
	global_load_dword v214, v205, s[0:1]
	global_load_dword v215, v205, s[0:1] offset:128
	v_or_b32_e32 v206, 0x12000, v32
	global_load_dword v216, v206, s[0:1]
	global_load_dword v217, v206, s[0:1] offset:128
	v_or_b32_e32 v207, 0x13000, v32
	global_load_dword v218, v207, s[0:1]
	global_load_dword v219, v207, s[0:1] offset:128
	v_or_b32_e32 v208, 0x18000, v32
	global_load_dword v220, v208, s[0:1]
	global_load_dword v221, v208, s[0:1] offset:128
	v_or_b32_e32 v209, 0x19000, v32
	global_load_dword v222, v209, s[0:1]
	global_load_dword v223, v209, s[0:1] offset:128
	v_or_b32_e32 v210, 0x1a000, v32
	global_load_dword v224, v210, s[0:1]
	global_load_dword v225, v210, s[0:1] offset:128
	v_or_b32_e32 v211, 0x1b000, v32
	global_load_dword v226, v211, s[0:1]
	global_load_dword v227, v211, s[0:1] offset:128
	s_waitcnt vmcnt(14)
	v_sub_f32_e32 v212, v212, v188
	v_sub_f32_e32 v213, v213, v188
	v_mul_f32_e32 v212, v189, v212
	v_mul_f32_e32 v213, v189, v213
	v_fma_f32 v212, v141, v212, v138
	v_fma_f32 v213, v139, v213, v140
	v_mul_f32_e32 v212, 0x3fd744fd, v212
	v_mul_f32_e32 v213, 0x3fd744fd, v213
	v_fmac_f32_e32 v212, v58, v137
	v_fmac_f32_e32 v213, v42, v136
	global_store_dword v204, v212, s[20:21]
	global_store_dword v204, v213, s[20:21] offset:128
	s_waitcnt vmcnt(14)
	v_sub_f32_e32 v214, v214, v190
	v_sub_f32_e32 v215, v215, v190
	v_mul_f32_e32 v214, v191, v214
	v_mul_f32_e32 v215, v191, v215
	v_fma_f32 v214, v141, v214, v138
	v_fma_f32 v215, v139, v215, v140
	v_mul_f32_e32 v214, 0x3fd744fd, v214
	v_mul_f32_e32 v215, 0x3fd744fd, v215
	v_fmac_f32_e32 v214, v59, v137
	v_fmac_f32_e32 v215, v43, v136
	global_store_dword v205, v214, s[20:21]
	global_store_dword v205, v215, s[20:21] offset:128
	s_waitcnt vmcnt(14)
	v_sub_f32_e32 v216, v216, v192
	v_sub_f32_e32 v217, v217, v192
	v_mul_f32_e32 v216, v193, v216
	v_mul_f32_e32 v217, v193, v217
	v_fma_f32 v216, v141, v216, v138
	v_fma_f32 v217, v139, v217, v140
	v_mul_f32_e32 v216, 0x3fd744fd, v216
	v_mul_f32_e32 v217, 0x3fd744fd, v217
	v_fmac_f32_e32 v216, v60, v137
	v_fmac_f32_e32 v217, v44, v136
	global_store_dword v206, v216, s[20:21]
	global_store_dword v206, v217, s[20:21] offset:128
	s_waitcnt vmcnt(14)
	v_sub_f32_e32 v218, v218, v194
	v_sub_f32_e32 v219, v219, v194
	v_mul_f32_e32 v218, v195, v218
	v_mul_f32_e32 v219, v195, v219
	v_fma_f32 v218, v141, v218, v138
	v_fma_f32 v219, v139, v219, v140
	v_mul_f32_e32 v218, 0x3fd744fd, v218
	v_mul_f32_e32 v219, 0x3fd744fd, v219
	v_fmac_f32_e32 v218, v61, v137
	v_fmac_f32_e32 v219, v45, v136
	global_store_dword v207, v218, s[20:21]
	global_store_dword v207, v219, s[20:21] offset:128
	s_waitcnt vmcnt(14)
	v_sub_f32_e32 v220, v220, v196
	v_sub_f32_e32 v221, v221, v196
	v_mul_f32_e32 v220, v197, v220
	v_mul_f32_e32 v221, v197, v221
	v_fma_f32 v220, v141, v220, v138
	v_fma_f32 v221, v139, v221, v140
	v_mul_f32_e32 v220, 0x3fd744fd, v220
	v_mul_f32_e32 v221, 0x3fd744fd, v221
	v_fmac_f32_e32 v220, v62, v137
	v_fmac_f32_e32 v221, v46, v136
	global_store_dword v208, v220, s[20:21]
	global_store_dword v208, v221, s[20:21] offset:128
	s_waitcnt vmcnt(14)
	v_sub_f32_e32 v222, v222, v198
	v_sub_f32_e32 v223, v223, v198
	v_mul_f32_e32 v222, v199, v222
	v_mul_f32_e32 v223, v199, v223
	v_fma_f32 v222, v141, v222, v138
	v_fma_f32 v223, v139, v223, v140
	v_mul_f32_e32 v222, 0x3fd744fd, v222
	v_mul_f32_e32 v223, 0x3fd744fd, v223
	v_fmac_f32_e32 v222, v63, v137
	v_fmac_f32_e32 v223, v47, v136
	global_store_dword v209, v222, s[20:21]
	global_store_dword v209, v223, s[20:21] offset:128
	s_waitcnt vmcnt(14)
	v_sub_f32_e32 v224, v224, v200
	v_sub_f32_e32 v225, v225, v200
	v_mul_f32_e32 v224, v201, v224
	v_mul_f32_e32 v225, v201, v225
	v_fma_f32 v224, v141, v224, v138
	v_fma_f32 v225, v139, v225, v140
	v_mul_f32_e32 v224, 0x3fd744fd, v224
	v_mul_f32_e32 v225, 0x3fd744fd, v225
	v_fmac_f32_e32 v224, v64, v137
	v_fmac_f32_e32 v225, v48, v136
	global_store_dword v210, v224, s[20:21]
	global_store_dword v210, v225, s[20:21] offset:128
	s_waitcnt vmcnt(14)
	v_sub_f32_e32 v226, v226, v202
	v_sub_f32_e32 v227, v227, v202
	v_mul_f32_e32 v226, v203, v226
	v_mul_f32_e32 v227, v203, v227
	v_fma_f32 v226, v141, v226, v138
	v_fma_f32 v227, v139, v227, v140
	v_mul_f32_e32 v226, 0x3fd744fd, v226
	v_mul_f32_e32 v227, 0x3fd744fd, v227
	v_fmac_f32_e32 v226, v65, v137
	v_fmac_f32_e32 v227, v49, v136
	global_store_dword v211, v226, s[20:21]
	global_store_dword v211, v227, s[20:21] offset:128
	v_mov_b32_e32 v188, 0
	v_mov_b32_e32 v189, 1.0
	v_mov_b32_e32 v190, 0
	v_mov_b32_e32 v191, 1.0
	v_mov_b32_e32 v192, 0
	v_mov_b32_e32 v193, 1.0
	v_mov_b32_e32 v194, 0
	v_mov_b32_e32 v195, 1.0
	v_mov_b32_e32 v196, 0
	v_mov_b32_e32 v197, 1.0
	v_mov_b32_e32 v198, 0
	v_mov_b32_e32 v199, 1.0
	v_mov_b32_e32 v200, 0
	v_mov_b32_e32 v201, 1.0
	v_mov_b32_e32 v202, 0
	v_mov_b32_e32 v203, 1.0
	s_and_b64 vcc, exec, s[38:39]
	s_cbranch_vccnz .Lres77_ns2
	global_load_dwordx2 v[188:189], v[130:131], off offset:256
	global_load_dwordx2 v[190:191], v[130:131], off offset:264
	global_load_dwordx2 v[192:193], v[130:131], off offset:272
	global_load_dwordx2 v[194:195], v[130:131], off offset:280
	global_load_dwordx2 v[196:197], v[130:131], off offset:320
	global_load_dwordx2 v[198:199], v[130:131], off offset:328
	global_load_dwordx2 v[200:201], v[130:131], off offset:336
	global_load_dwordx2 v[202:203], v[130:131], off offset:344
.Lres77_ns2:
	v_or_b32_e32 v204, 0x20000, v32
	global_load_dword v212, v204, s[0:1]
	global_load_dword v213, v204, s[0:1] offset:128
	v_or_b32_e32 v205, 0x21000, v32
	global_load_dword v214, v205, s[0:1]
	global_load_dword v215, v205, s[0:1] offset:128
	v_or_b32_e32 v206, 0x22000, v32
	global_load_dword v216, v206, s[0:1]
	global_load_dword v217, v206, s[0:1] offset:128
	v_or_b32_e32 v207, 0x23000, v32
	global_load_dword v218, v207, s[0:1]
	global_load_dword v219, v207, s[0:1] offset:128
	v_or_b32_e32 v208, 0x28000, v32
	global_load_dword v220, v208, s[0:1]
	global_load_dword v221, v208, s[0:1] offset:128
	v_or_b32_e32 v209, 0x29000, v32
	global_load_dword v222, v209, s[0:1]
	global_load_dword v223, v209, s[0:1] offset:128
	v_or_b32_e32 v210, 0x2a000, v32
	global_load_dword v224, v210, s[0:1]
	global_load_dword v225, v210, s[0:1] offset:128
	v_or_b32_e32 v211, 0x2b000, v32
	global_load_dword v226, v211, s[0:1]
	global_load_dword v227, v211, s[0:1] offset:128
	s_waitcnt vmcnt(14)
	v_sub_f32_e32 v212, v212, v188
	v_sub_f32_e32 v213, v213, v188
	v_mul_f32_e32 v212, v189, v212
	v_mul_f32_e32 v213, v189, v213
	v_fma_f32 v212, v141, v212, v138
	v_fma_f32 v213, v139, v213, v140
	v_mul_f32_e32 v212, 0x3fd744fd, v212
	v_mul_f32_e32 v213, 0x3fd744fd, v213
	v_fmac_f32_e32 v212, v16, v137
	v_fmac_f32_e32 v213, v0, v136
	global_store_dword v204, v212, s[20:21]
	global_store_dword v204, v213, s[20:21] offset:128
	s_waitcnt vmcnt(14)
	v_sub_f32_e32 v214, v214, v190
	v_sub_f32_e32 v215, v215, v190
	v_mul_f32_e32 v214, v191, v214
	v_mul_f32_e32 v215, v191, v215
	v_fma_f32 v214, v141, v214, v138
	v_fma_f32 v215, v139, v215, v140
	v_mul_f32_e32 v214, 0x3fd744fd, v214
	v_mul_f32_e32 v215, 0x3fd744fd, v215
	v_fmac_f32_e32 v214, v17, v137
	v_fmac_f32_e32 v215, v1, v136
	global_store_dword v205, v214, s[20:21]
	global_store_dword v205, v215, s[20:21] offset:128
	s_waitcnt vmcnt(14)
	v_sub_f32_e32 v216, v216, v192
	v_sub_f32_e32 v217, v217, v192
	v_mul_f32_e32 v216, v193, v216
	v_mul_f32_e32 v217, v193, v217
	v_fma_f32 v216, v141, v216, v138
	v_fma_f32 v217, v139, v217, v140
	v_mul_f32_e32 v216, 0x3fd744fd, v216
	v_mul_f32_e32 v217, 0x3fd744fd, v217
	v_fmac_f32_e32 v216, v18, v137
	v_fmac_f32_e32 v217, v2, v136
	global_store_dword v206, v216, s[20:21]
	global_store_dword v206, v217, s[20:21] offset:128
	s_waitcnt vmcnt(14)
	v_sub_f32_e32 v218, v218, v194
	v_sub_f32_e32 v219, v219, v194
	v_mul_f32_e32 v218, v195, v218
	v_mul_f32_e32 v219, v195, v219
	v_fma_f32 v218, v141, v218, v138
	v_fma_f32 v219, v139, v219, v140
	v_mul_f32_e32 v218, 0x3fd744fd, v218
	v_mul_f32_e32 v219, 0x3fd744fd, v219
	v_fmac_f32_e32 v218, v19, v137
	v_fmac_f32_e32 v219, v3, v136
	global_store_dword v207, v218, s[20:21]
	global_store_dword v207, v219, s[20:21] offset:128
	s_waitcnt vmcnt(14)
	v_sub_f32_e32 v220, v220, v196
	v_sub_f32_e32 v221, v221, v196
	v_mul_f32_e32 v220, v197, v220
	v_mul_f32_e32 v221, v197, v221
	v_fma_f32 v220, v141, v220, v138
	v_fma_f32 v221, v139, v221, v140
	v_mul_f32_e32 v220, 0x3fd744fd, v220
	v_mul_f32_e32 v221, 0x3fd744fd, v221
	v_fmac_f32_e32 v220, v20, v137
	v_fmac_f32_e32 v221, v4, v136
	global_store_dword v208, v220, s[20:21]
	global_store_dword v208, v221, s[20:21] offset:128
	s_waitcnt vmcnt(14)
	v_sub_f32_e32 v222, v222, v198
	v_sub_f32_e32 v223, v223, v198
	v_mul_f32_e32 v222, v199, v222
	v_mul_f32_e32 v223, v199, v223
	v_fma_f32 v222, v141, v222, v138
	v_fma_f32 v223, v139, v223, v140
	v_mul_f32_e32 v222, 0x3fd744fd, v222
	v_mul_f32_e32 v223, 0x3fd744fd, v223
	v_fmac_f32_e32 v222, v21, v137
	v_fmac_f32_e32 v223, v5, v136
	global_store_dword v209, v222, s[20:21]
	global_store_dword v209, v223, s[20:21] offset:128
	s_waitcnt vmcnt(14)
	v_sub_f32_e32 v224, v224, v200
	v_sub_f32_e32 v225, v225, v200
	v_mul_f32_e32 v224, v201, v224
	v_mul_f32_e32 v225, v201, v225
	v_fma_f32 v224, v141, v224, v138
	v_fma_f32 v225, v139, v225, v140
	v_mul_f32_e32 v224, 0x3fd744fd, v224
	v_mul_f32_e32 v225, 0x3fd744fd, v225
	v_fmac_f32_e32 v224, v22, v137
	v_fmac_f32_e32 v225, v6, v136
	global_store_dword v210, v224, s[20:21]
	global_store_dword v210, v225, s[20:21] offset:128
	s_waitcnt vmcnt(14)
	v_sub_f32_e32 v226, v226, v202
	v_sub_f32_e32 v227, v227, v202
	v_mul_f32_e32 v226, v203, v226
	v_mul_f32_e32 v227, v203, v227
	v_fma_f32 v226, v141, v226, v138
	v_fma_f32 v227, v139, v227, v140
	v_mul_f32_e32 v226, 0x3fd744fd, v226
	v_mul_f32_e32 v227, 0x3fd744fd, v227
	v_fmac_f32_e32 v226, v23, v137
	v_fmac_f32_e32 v227, v7, v136
	global_store_dword v211, v226, s[20:21]
	global_store_dword v211, v227, s[20:21] offset:128
	v_mov_b32_e32 v188, 0
	v_mov_b32_e32 v189, 1.0
	v_mov_b32_e32 v190, 0
	v_mov_b32_e32 v191, 1.0
	v_mov_b32_e32 v192, 0
	v_mov_b32_e32 v193, 1.0
	v_mov_b32_e32 v194, 0
	v_mov_b32_e32 v195, 1.0
	v_mov_b32_e32 v196, 0
	v_mov_b32_e32 v197, 1.0
	v_mov_b32_e32 v198, 0
	v_mov_b32_e32 v199, 1.0
	v_mov_b32_e32 v200, 0
	v_mov_b32_e32 v201, 1.0
	v_mov_b32_e32 v202, 0
	v_mov_b32_e32 v203, 1.0
	s_and_b64 vcc, exec, s[38:39]
	s_cbranch_vccnz .Lres77_ns3
	global_load_dwordx2 v[188:189], v[130:131], off offset:384
	global_load_dwordx2 v[190:191], v[130:131], off offset:392
	global_load_dwordx2 v[192:193], v[130:131], off offset:400
	global_load_dwordx2 v[194:195], v[130:131], off offset:408
	global_load_dwordx2 v[196:197], v[130:131], off offset:448
	global_load_dwordx2 v[198:199], v[130:131], off offset:456
	global_load_dwordx2 v[200:201], v[130:131], off offset:464
	global_load_dwordx2 v[202:203], v[130:131], off offset:472
.Lres77_ns3:
	v_or_b32_e32 v204, 0x30000, v32
	global_load_dword v212, v204, s[0:1]
	global_load_dword v213, v204, s[0:1] offset:128
	v_or_b32_e32 v205, 0x31000, v32
	global_load_dword v214, v205, s[0:1]
	global_load_dword v215, v205, s[0:1] offset:128
	v_or_b32_e32 v206, 0x32000, v32
	global_load_dword v216, v206, s[0:1]
	global_load_dword v217, v206, s[0:1] offset:128
	v_or_b32_e32 v207, 0x33000, v32
	global_load_dword v218, v207, s[0:1]
	global_load_dword v219, v207, s[0:1] offset:128
	v_or_b32_e32 v208, 0x38000, v32
	global_load_dword v220, v208, s[0:1]
	global_load_dword v221, v208, s[0:1] offset:128
	v_or_b32_e32 v209, 0x39000, v32
	global_load_dword v222, v209, s[0:1]
	global_load_dword v223, v209, s[0:1] offset:128
	v_or_b32_e32 v210, 0x3a000, v32
	global_load_dword v224, v210, s[0:1]
	global_load_dword v225, v210, s[0:1] offset:128
	v_or_b32_e32 v211, 0x3b000, v32
	global_load_dword v226, v211, s[0:1]
	global_load_dword v227, v211, s[0:1] offset:128
	s_waitcnt vmcnt(14)
	v_sub_f32_e32 v212, v212, v188
	v_sub_f32_e32 v213, v213, v188
	v_mul_f32_e32 v212, v189, v212
	v_mul_f32_e32 v213, v189, v213
	v_fma_f32 v212, v141, v212, v138
	v_fma_f32 v213, v139, v213, v140
	v_mul_f32_e32 v212, 0x3fd744fd, v212
	v_mul_f32_e32 v213, 0x3fd744fd, v213
	v_fmac_f32_e32 v212, v24, v137
	v_fmac_f32_e32 v213, v8, v136
	global_store_dword v204, v212, s[20:21]
	global_store_dword v204, v213, s[20:21] offset:128
	s_waitcnt vmcnt(14)
	v_sub_f32_e32 v214, v214, v190
	v_sub_f32_e32 v215, v215, v190
	v_mul_f32_e32 v214, v191, v214
	v_mul_f32_e32 v215, v191, v215
	v_fma_f32 v214, v141, v214, v138
	v_fma_f32 v215, v139, v215, v140
	v_mul_f32_e32 v214, 0x3fd744fd, v214
	v_mul_f32_e32 v215, 0x3fd744fd, v215
	v_fmac_f32_e32 v214, v25, v137
	v_fmac_f32_e32 v215, v9, v136
	global_store_dword v205, v214, s[20:21]
	global_store_dword v205, v215, s[20:21] offset:128
	s_waitcnt vmcnt(14)
	v_sub_f32_e32 v216, v216, v192
	v_sub_f32_e32 v217, v217, v192
	v_mul_f32_e32 v216, v193, v216
	v_mul_f32_e32 v217, v193, v217
	v_fma_f32 v216, v141, v216, v138
	v_fma_f32 v217, v139, v217, v140
	v_mul_f32_e32 v216, 0x3fd744fd, v216
	v_mul_f32_e32 v217, 0x3fd744fd, v217
	v_fmac_f32_e32 v216, v26, v137
	v_fmac_f32_e32 v217, v10, v136
	global_store_dword v206, v216, s[20:21]
	global_store_dword v206, v217, s[20:21] offset:128
	s_waitcnt vmcnt(14)
	v_sub_f32_e32 v218, v218, v194
	v_sub_f32_e32 v219, v219, v194
	v_mul_f32_e32 v218, v195, v218
	v_mul_f32_e32 v219, v195, v219
	v_fma_f32 v218, v141, v218, v138
	v_fma_f32 v219, v139, v219, v140
	v_mul_f32_e32 v218, 0x3fd744fd, v218
	v_mul_f32_e32 v219, 0x3fd744fd, v219
	v_fmac_f32_e32 v218, v27, v137
	v_fmac_f32_e32 v219, v11, v136
	global_store_dword v207, v218, s[20:21]
	global_store_dword v207, v219, s[20:21] offset:128
	s_waitcnt vmcnt(14)
	v_sub_f32_e32 v220, v220, v196
	v_sub_f32_e32 v221, v221, v196
	v_mul_f32_e32 v220, v197, v220
	v_mul_f32_e32 v221, v197, v221
	v_fma_f32 v220, v141, v220, v138
	v_fma_f32 v221, v139, v221, v140
	v_mul_f32_e32 v220, 0x3fd744fd, v220
	v_mul_f32_e32 v221, 0x3fd744fd, v221
	v_fmac_f32_e32 v220, v28, v137
	v_fmac_f32_e32 v221, v12, v136
	global_store_dword v208, v220, s[20:21]
	global_store_dword v208, v221, s[20:21] offset:128
	s_waitcnt vmcnt(14)
	v_sub_f32_e32 v222, v222, v198
	v_sub_f32_e32 v223, v223, v198
	v_mul_f32_e32 v222, v199, v222
	v_mul_f32_e32 v223, v199, v223
	v_fma_f32 v222, v141, v222, v138
	v_fma_f32 v223, v139, v223, v140
	v_mul_f32_e32 v222, 0x3fd744fd, v222
	v_mul_f32_e32 v223, 0x3fd744fd, v223
	v_fmac_f32_e32 v222, v29, v137
	v_fmac_f32_e32 v223, v13, v136
	global_store_dword v209, v222, s[20:21]
	global_store_dword v209, v223, s[20:21] offset:128
	s_waitcnt vmcnt(14)
	v_sub_f32_e32 v224, v224, v200
	v_sub_f32_e32 v225, v225, v200
	v_mul_f32_e32 v224, v201, v224
	v_mul_f32_e32 v225, v201, v225
	v_fma_f32 v224, v141, v224, v138
	v_fma_f32 v225, v139, v225, v140
	v_mul_f32_e32 v224, 0x3fd744fd, v224
	v_mul_f32_e32 v225, 0x3fd744fd, v225
	v_fmac_f32_e32 v224, v30, v137
	v_fmac_f32_e32 v225, v14, v136
	global_store_dword v210, v224, s[20:21]
	global_store_dword v210, v225, s[20:21] offset:128
	s_waitcnt vmcnt(14)
	v_sub_f32_e32 v226, v226, v202
	v_sub_f32_e32 v227, v227, v202
	v_mul_f32_e32 v226, v203, v226
	v_mul_f32_e32 v227, v203, v227
	v_fma_f32 v226, v141, v226, v138
	v_fma_f32 v227, v139, v227, v140
	v_mul_f32_e32 v226, 0x3fd744fd, v226
	v_mul_f32_e32 v227, 0x3fd744fd, v227
	v_fmac_f32_e32 v226, v31, v137
	v_fmac_f32_e32 v227, v15, v136
	global_store_dword v211, v226, s[20:21]
	global_store_dword v211, v227, s[20:21] offset:128
	s_branch .Lres_tail_77
